# mlA: next item's K/V row loads issued at the top of the current item into a second register set (a full item of cover); dead per-item gate loads removed
# speedup vs baseline: 1.0068x; 1.0048x over previous
.Lmla_g_done:
	s_waitcnt lgkmcnt(0)
	s_barrier
	s_mov_b32 s99, 0
	s_waitcnt vmcnt(0)
	v_mov_b32_e32 v88, v16
	v_mov_b32_e32 v89, v17
	v_mov_b32_e32 v90, v18
	v_mov_b32_e32 v91, v19
	v_mov_b32_e32 v92, v20
	v_mov_b32_e32 v93, v21
	v_mov_b32_e32 v94, v22
	v_mov_b32_e32 v95, v23
	v_mov_b32_e32 v96, v24
	v_mov_b32_e32 v97, v25
	v_mov_b32_e32 v98, v26
	v_mov_b32_e32 v99, v27
	s_mov_b32 s6, s82
	s_branch .LBB0_735

.LBB0_738:
	s_or_b64 exec, exec, s[2:3]
	v_readlane_b32 s2, v254, 33
	s_waitcnt vmcnt(0) lgkmcnt(0)
	v_mov_b32_e32 v16, v88
	v_mov_b32_e32 v17, v89
	v_mov_b32_e32 v18, v90
	v_mov_b32_e32 v19, v91
	v_mov_b32_e32 v20, v92
	v_mov_b32_e32 v21, v93
	v_mov_b32_e32 v22, v94
	v_mov_b32_e32 v23, v95
	v_mov_b32_e32 v24, v96
	v_mov_b32_e32 v25, v97
	v_mov_b32_e32 v26, v98
	v_mov_b32_e32 v27, v99
	s_add_i32 s36, s6, s86
	s_cmpk_gt_i32 s36, 0x87f
	s_cbranch_scc1 .Lmla_pf_none
	s_mul_hi_i32 s7, s36, 0x78787879
	s_lshr_b32 s8, s7, 31
	s_ashr_i32 s40, s7, 5
	s_add_i32 s40, s40, s8
	s_mul_i32 s7, s40, 0x44
	s_sub_i32 s37, s36, s7
	s_mul_i32 s7, s40, 0xffffffbc
	s_add_i32 s10, s36, s7
	s_and_b32 s7, s40, 1
	s_ashr_i32 s39, s40, 3
	s_cmp_gt_i32 s10, 3
	s_cselect_b64 s[10:11], -1, 0
	s_mov_b64 s[8:9], -1
	s_and_b64 vcc, exec, s[10:11]
	s_cbranch_vccz .LBB0_745
	s_cmp_eq_u32 s7, 0
	s_cbranch_scc1 .LBB0_742
	s_mul_i32 s8, s40, 0x1100
	s_add_i32 s8, s8, s18
	v_add_u32_e32 v0, s8, v52
	v_add_u32_e32 v0, 0x10ff, v0
	s_mov_b64 s[8:9], 0

.LBB0_751:
	s_bfe_u32 s41, s40, 0x20001
	v_mov_b64_e32 v[2:3], s[30:31]
	v_mad_i64_i32 v[0:1], s[8:9], v0, s33, v[2:3]
	s_lshl_b32 s34, s41, 7
	v_lshl_add_u64 v[2:3], v[0:1], 0, s[34:35]
	v_mov_b32_e32 v41, v113
	s_lshl_b32 s34, s41, 8
	v_lshl_add_u64 v[2:3], v[2:3], 0, v[40:41]
	v_lshl_add_u64 v[0:1], v[0:1], 0, s[34:35]
	v_lshl_add_u64 v[0:1], v[0:1], 0, v[40:41]
	global_load_dwordx4 v[88:91], v[2:3], off offset:512
	global_load_dwordx4 v[92:95], v[0:1], off offset:1024
	global_load_dwordx4 v[96:99], v[0:1], off offset:1152
.Lmla_pf_none:
	ds_write_b16 v54, v20 offset:27648
	ds_write_b16_d16_hi v54, v20 offset:27792
	ds_write_b16 v54, v21 offset:27936
	ds_write_b16_d16_hi v54, v21 offset:28080
	ds_write_b16 v54, v22 offset:28224
	ds_write_b16_d16_hi v54, v22 offset:28368
	ds_write_b16 v54, v23 offset:28512
	ds_write_b16_d16_hi v54, v23 offset:28656
	ds_write_b16 v54, v24 offset:36864
	ds_write_b16_d16_hi v54, v24 offset:37008
	ds_write_b16 v54, v25 offset:37152
	ds_write_b16_d16_hi v54, v25 offset:37296
	ds_write_b16 v54, v26 offset:37440
	ds_write_b16_d16_hi v54, v26 offset:37584
	ds_write_b16 v54, v27 offset:37728
	ds_write_b16_d16_hi v54, v27 offset:37872
	v_mov_b32_e32 v0, s2
	s_waitcnt lgkmcnt(0)
	s_barrier
	ds_read_b32 v1, v32 offset:64512
	ds_read_b32 v0, v0
	s_add_i32 s36, s6, s86
	s_cmpk_gt_i32 s36, 0x87f
	s_cselect_b64 s[2:3], -1, 0
	s_and_b64 vcc, exec, s[2:3]
	s_waitcnt lgkmcnt(0)
	v_sub_f32_e32 v0, v1, v0
	v_mul_f32_e32 v0, 0x3fb8aa3b, v0
	v_exp_f32_e32 v0, v0
	v_lshlrev_b32_e32 v1, 16, v16
	v_mul_f32_e32 v1, v0, v1
	v_cvt_pk_bf16_f32 v1, v1, s0
	ds_write_b16 v54, v1 offset:18432
	v_and_b32_e32 v1, 0xffff0000, v16
	v_mul_f32_e32 v1, v0, v1
	v_cvt_pk_bf16_f32 v1, v1, s0
	ds_write_b16 v54, v1 offset:18576
	v_lshlrev_b32_e32 v1, 16, v17
	v_mul_f32_e32 v1, v0, v1
	v_cvt_pk_bf16_f32 v1, v1, s0
	ds_write_b16 v54, v1 offset:18720
	v_and_b32_e32 v1, 0xffff0000, v17
	v_mul_f32_e32 v1, v0, v1
	v_cvt_pk_bf16_f32 v1, v1, s0
	ds_write_b16 v54, v1 offset:18864
	v_lshlrev_b32_e32 v1, 16, v18
	v_mul_f32_e32 v1, v0, v1
	v_cvt_pk_bf16_f32 v1, v1, s0
	ds_write_b16 v54, v1 offset:19008
	v_and_b32_e32 v1, 0xffff0000, v18
	v_mul_f32_e32 v1, v0, v1
	v_cvt_pk_bf16_f32 v1, v1, s0
	ds_write_b16 v54, v1 offset:19152
	v_lshlrev_b32_e32 v1, 16, v19
	v_mul_f32_e32 v1, v0, v1
	v_cvt_pk_bf16_f32 v1, v1, s0
	ds_write_b16 v54, v1 offset:19296
	v_and_b32_e32 v1, 0xffff0000, v19
	v_mul_f32_e32 v0, v0, v1
	v_cvt_pk_bf16_f32 v0, v0, s0
	ds_write_b16 v54, v0 offset:19440
